# phase-0 adaLN GEMV: weight rows of the next 8-row step are requested one step ahead (prefetch registers, copied at the top of the step)
# baseline (speedup 1.0000x reference)
; #define LAS __attribute__((address_space(3)))
; __global__ void __launch_bounds__(NWAVES * 64, 2) mk_fwd(Args args) {
;     ...
;                     const float* wp = args.in[9] + ((size_t)lm * DM + k0) * (3 * DM) + col;
; #pragma unroll 2
;                     for (int k = 0; k < 128; k += 4) {
;                         const f32x2 wa = *(const f32x2*)(wp + (size_t)(k + 0) * (3 * DM)), wb = *(const f32x2*)(wp + (size_t)(k + 1) * (3 * DM));
;                         const f32x2 wc = *(const f32x2*)(wp + (size_t)(k + 2) * (3 * DM)), wd = *(const f32x2*)(wp + (size_t)(k + 3) * (3 * DM));
; #pragma unroll
;                         for (int r2 = 0; r2 < 20; ++r2) { const f32x4 cv = *(LAS const f32x4*)(cs + r2 * 128 + k);
;                             acc[r2] = wa * cv.x + acc[r2]; acc[r2] = wb * cv.y + acc[r2]; acc[r2] = wc * cv.z + acc[r2]; acc[r2] = wd * cv.w + acc[r2]; }
.LBB0_28:
	s_or_b64 exec, exec, s[16:17]
	v_mad_i64_i32 v[26:27], s[0:1], s38, v74, v[24:25]
	s_mov_b32 s0, -4
	s_mov_b32 s1, 0
	s_waitcnt lgkmcnt(0)
	s_barrier
	s_mov_b32 s16, 0xfffac000
	v_add_co_u32_e32 v112, vcc, s16, v26
	s_mov_b32 s16, 0xfffb8000
	s_nop 0
	v_addc_co_u32_e32 v113, vcc, -1, v27, vcc
	global_load_dwordx2 v[96:97], v[112:113], off
	v_add_co_u32_e32 v112, vcc, s16, v26
	s_mov_b32 s16, 0xfffc4000
	s_nop 0
	v_addc_co_u32_e32 v113, vcc, -1, v27, vcc
	global_load_dwordx2 v[98:99], v[112:113], off
	v_add_co_u32_e32 v112, vcc, s16, v26
	s_mov_b32 s16, 0xfffd0000
	s_nop 0
	v_addc_co_u32_e32 v113, vcc, -1, v27, vcc
	global_load_dwordx2 v[100:101], v[112:113], off
	v_add_co_u32_e32 v112, vcc, s16, v26
	s_nop 1
	v_addc_co_u32_e32 v113, vcc, -1, v27, vcc
	global_load_dwordx2 v[102:103], v[112:113], off
	s_mov_b32 s16, 0xfffdc000
	v_add_co_u32_e32 v104, vcc, s16, v26
	s_mov_b32 s16, 0xfffe8000
	s_nop 0
	v_addc_co_u32_e32 v105, vcc, -1, v27, vcc
	v_add_co_u32_e32 v106, vcc, s16, v26
	global_load_dwordx2 v[104:105], v[104:105], off
	s_nop 0
	v_addc_co_u32_e32 v107, vcc, -1, v27, vcc
	s_mov_b32 s16, 0xffff4000
	global_load_dwordx2 v[106:107], v[106:107], off
	v_add_co_u32_e32 v108, vcc, s16, v26
	s_nop 1
	v_addc_co_u32_e32 v109, vcc, -1, v27, vcc
	global_load_dwordx2 v[108:109], v[108:109], off
	s_nop 0
	global_load_dwordx2 v[110:111], v[26:27], off
.LBB0_29:
	s_waitcnt vmcnt(0)
	v_mov_b64_e32 v[68:69], v[96:97]
	v_mov_b64_e32 v[80:81], v[98:99]
	v_mov_b64_e32 v[82:83], v[100:101]
	v_mov_b64_e32 v[84:85], v[102:103]
	v_mov_b64_e32 v[88:89], v[104:105]
	v_mov_b64_e32 v[90:91], v[106:107]
	v_mov_b64_e32 v[92:93], v[108:109]
	v_mov_b64_e32 v[94:95], v[110:111]
	s_mov_b64 s[16:17], 0x60000
	v_lshl_add_u64 v[26:27], v[26:27], 0, s[16:17]
	v_mov_b32_e32 v15, s1
	ds_read_b128 v[76:79], v15
	ds_read_b128 v[6:9], v15 offset:16
	s_mov_b32 s16, 0xfffdc000
	s_add_i32 s0, s0, 8
	s_add_i32 s1, s1, 32
	s_cmpk_gt_u32 s0, 0x7b
	s_cbranch_scc1 .Lgemv_nopf
	s_mov_b32 s16, 0xfffac000
	v_add_co_u32_e32 v112, vcc, s16, v26
	s_mov_b32 s16, 0xfffb8000
	s_nop 0
	v_addc_co_u32_e32 v113, vcc, -1, v27, vcc
	global_load_dwordx2 v[96:97], v[112:113], off
	v_add_co_u32_e32 v112, vcc, s16, v26
	s_mov_b32 s16, 0xfffc4000
	s_nop 0
	v_addc_co_u32_e32 v113, vcc, -1, v27, vcc
	global_load_dwordx2 v[98:99], v[112:113], off
	v_add_co_u32_e32 v112, vcc, s16, v26
	s_mov_b32 s16, 0xfffd0000
	s_nop 0
	v_addc_co_u32_e32 v113, vcc, -1, v27, vcc
	global_load_dwordx2 v[100:101], v[112:113], off
	v_add_co_u32_e32 v112, vcc, s16, v26
	s_nop 1
	v_addc_co_u32_e32 v113, vcc, -1, v27, vcc
	global_load_dwordx2 v[102:103], v[112:113], off
	s_mov_b32 s16, 0xfffdc000
	v_add_co_u32_e32 v104, vcc, s16, v26
	s_mov_b32 s16, 0xfffe8000
	s_nop 0
	v_addc_co_u32_e32 v105, vcc, -1, v27, vcc
	v_add_co_u32_e32 v106, vcc, s16, v26
	global_load_dwordx2 v[104:105], v[104:105], off
	s_nop 0
	v_addc_co_u32_e32 v107, vcc, -1, v27, vcc
	s_mov_b32 s16, 0xffff4000
	global_load_dwordx2 v[106:107], v[106:107], off
	v_add_co_u32_e32 v108, vcc, s16, v26
	s_nop 1
	v_addc_co_u32_e32 v109, vcc, -1, v27, vcc
	global_load_dwordx2 v[108:109], v[108:109], off
	s_nop 0
	global_load_dwordx2 v[110:111], v[26:27], off
.Lgemv_nopf:
	s_cmpk_gt_u32 s0, 0x7b
	s_waitcnt lgkmcnt(1)
	v_pk_fma_f32 v[66:67], v[68:69], v[76:77], v[66:67] op_sel_hi:[1,0,1]
	v_pk_fma_f32 v[66:67], v[80:81], v[76:77], v[66:67] op_sel:[0,1,0]
	v_mov_b32_e32 v76, v79
	v_pk_fma_f32 v[66:67], v[82:83], v[78:79], v[66:67] op_sel_hi:[1,0,1]
	v_pk_fma_f32 v[66:67], v[84:85], v[76:77], v[66:67] op_sel_hi:[1,0,1]
	ds_read_b128 v[76:79], v15 offset:512
	s_waitcnt lgkmcnt(0)
	v_pk_fma_f32 v[64:65], v[68:69], v[76:77], v[64:65] op_sel_hi:[1,0,1]
	s_nop 0
	v_pk_fma_f32 v[64:65], v[80:81], v[76:77], v[64:65] op_sel:[0,1,0]
	v_mov_b32_e32 v76, v79
	v_pk_fma_f32 v[64:65], v[82:83], v[78:79], v[64:65] op_sel_hi:[1,0,1]
	s_nop 0
	v_pk_fma_f32 v[64:65], v[84:85], v[76:77], v[64:65] op_sel_hi:[1,0,1]
	ds_read_b128 v[76:79], v15 offset:1024
	s_waitcnt lgkmcnt(0)
	v_pk_fma_f32 v[62:63], v[68:69], v[76:77], v[62:63] op_sel_hi:[1,0,1]
	s_nop 0
	v_pk_fma_f32 v[62:63], v[80:81], v[76:77], v[62:63] op_sel:[0,1,0]
	v_mov_b32_e32 v76, v79
	v_pk_fma_f32 v[62:63], v[82:83], v[78:79], v[62:63] op_sel_hi:[1,0,1]
	s_nop 0
	v_pk_fma_f32 v[62:63], v[84:85], v[76:77], v[62:63] op_sel_hi:[1,0,1]
	ds_read_b128 v[76:79], v15 offset:1536
	s_waitcnt lgkmcnt(0)
	v_pk_fma_f32 v[60:61], v[68:69], v[76:77], v[60:61] op_sel_hi:[1,0,1]
	s_nop 0
	v_pk_fma_f32 v[60:61], v[80:81], v[76:77], v[60:61] op_sel:[0,1,0]
	v_mov_b32_e32 v76, v79
	v_pk_fma_f32 v[60:61], v[82:83], v[78:79], v[60:61] op_sel_hi:[1,0,1]
	s_nop 0
	v_pk_fma_f32 v[60:61], v[84:85], v[76:77], v[60:61] op_sel_hi:[1,0,1]
	ds_read_b128 v[76:79], v15 offset:2048
	s_waitcnt lgkmcnt(0)
	v_pk_fma_f32 v[58:59], v[68:69], v[76:77], v[58:59] op_sel_hi:[1,0,1]
	s_nop 0
	v_pk_fma_f32 v[58:59], v[80:81], v[76:77], v[58:59] op_sel:[0,1,0]
	v_mov_b32_e32 v76, v79
	v_pk_fma_f32 v[58:59], v[82:83], v[78:79], v[58:59] op_sel_hi:[1,0,1]
	s_nop 0
	v_pk_fma_f32 v[58:59], v[84:85], v[76:77], v[58:59] op_sel_hi:[1,0,1]
	ds_read_b128 v[76:79], v15 offset:2560
	s_waitcnt lgkmcnt(0)
	v_pk_fma_f32 v[56:57], v[68:69], v[76:77], v[56:57] op_sel_hi:[1,0,1]
	s_nop 0
	v_pk_fma_f32 v[56:57], v[80:81], v[76:77], v[56:57] op_sel:[0,1,0]
	v_mov_b32_e32 v76, v79
	v_pk_fma_f32 v[56:57], v[82:83], v[78:79], v[56:57] op_sel_hi:[1,0,1]
	s_nop 0
	v_pk_fma_f32 v[56:57], v[84:85], v[76:77], v[56:57] op_sel_hi:[1,0,1]
	ds_read_b128 v[76:79], v15 offset:3072
	s_waitcnt lgkmcnt(0)
; #define LAS __attribute__((address_space(3)))
; __global__ void __launch_bounds__(NWAVES * 64, 2) mk_fwd(Args args) {
;     ...
;                     const float* wp = args.in[9] + ((size_t)lm * DM + k0) * (3 * DM) + col;
; #pragma unroll 2
;                     for (int k = 0; k < 128; k += 4) {
;                         const f32x2 wa = *(const f32x2*)(wp + (size_t)(k + 0) * (3 * DM)), wb = *(const f32x2*)(wp + (size_t)(k + 1) * (3 * DM));
;                         const f32x2 wc = *(const f32x2*)(wp + (size_t)(k + 2) * (3 * DM)), wd = *(const f32x2*)(wp + (size_t)(k + 3) * (3 * DM));
; #pragma unroll
;                         for (int r2 = 0; r2 < 20; ++r2) { const f32x4 cv = *(LAS const f32x4*)(cs + r2 * 128 + k);
;                             acc[r2] = wa * cv.x + acc[r2]; acc[r2] = wb * cv.y + acc[r2]; acc[r2] = wc * cv.z + acc[r2]; acc[r2] = wd * cv.w + acc[r2]; }
	v_pk_fma_f32 v[54:55], v[68:69], v[76:77], v[54:55] op_sel_hi:[1,0,1]
	s_nop 0
	v_pk_fma_f32 v[54:55], v[80:81], v[76:77], v[54:55] op_sel:[0,1,0]
	v_mov_b32_e32 v76, v79
	v_pk_fma_f32 v[54:55], v[82:83], v[78:79], v[54:55] op_sel_hi:[1,0,1]
	s_nop 0
	v_pk_fma_f32 v[54:55], v[84:85], v[76:77], v[54:55] op_sel_hi:[1,0,1]
	ds_read_b128 v[76:79], v15 offset:3584
	s_waitcnt lgkmcnt(0)
	v_pk_fma_f32 v[52:53], v[68:69], v[76:77], v[52:53] op_sel_hi:[1,0,1]
	s_nop 0
	v_pk_fma_f32 v[52:53], v[80:81], v[76:77], v[52:53] op_sel:[0,1,0]
	v_mov_b32_e32 v76, v79
	v_pk_fma_f32 v[52:53], v[82:83], v[78:79], v[52:53] op_sel_hi:[1,0,1]
	s_nop 0
	v_pk_fma_f32 v[52:53], v[84:85], v[76:77], v[52:53] op_sel_hi:[1,0,1]
	ds_read_b128 v[76:79], v15 offset:4096
	s_waitcnt lgkmcnt(0)
	v_pk_fma_f32 v[50:51], v[68:69], v[76:77], v[50:51] op_sel_hi:[1,0,1]
	s_nop 0
	v_pk_fma_f32 v[50:51], v[80:81], v[76:77], v[50:51] op_sel:[0,1,0]
	v_mov_b32_e32 v76, v79
	v_pk_fma_f32 v[50:51], v[82:83], v[78:79], v[50:51] op_sel_hi:[1,0,1]
	s_nop 0
	v_pk_fma_f32 v[50:51], v[84:85], v[76:77], v[50:51] op_sel_hi:[1,0,1]
	ds_read_b128 v[76:79], v15 offset:4608
	s_waitcnt lgkmcnt(0)
	v_pk_fma_f32 v[48:49], v[68:69], v[76:77], v[48:49] op_sel_hi:[1,0,1]
	s_nop 0
	v_pk_fma_f32 v[48:49], v[80:81], v[76:77], v[48:49] op_sel:[0,1,0]
	v_mov_b32_e32 v76, v79
	v_pk_fma_f32 v[48:49], v[82:83], v[78:79], v[48:49] op_sel_hi:[1,0,1]
	s_nop 0
	v_pk_fma_f32 v[48:49], v[84:85], v[76:77], v[48:49] op_sel_hi:[1,0,1]
	ds_read_b128 v[76:79], v15 offset:5120
	s_waitcnt lgkmcnt(0)
	v_pk_fma_f32 v[46:47], v[68:69], v[76:77], v[46:47] op_sel_hi:[1,0,1]
	s_nop 0
	v_pk_fma_f32 v[46:47], v[80:81], v[76:77], v[46:47] op_sel:[0,1,0]
	v_mov_b32_e32 v76, v79
	v_pk_fma_f32 v[46:47], v[82:83], v[78:79], v[46:47] op_sel_hi:[1,0,1]
	s_nop 0
	v_pk_fma_f32 v[46:47], v[84:85], v[76:77], v[46:47] op_sel_hi:[1,0,1]
	ds_read_b128 v[76:79], v15 offset:5632
	s_waitcnt lgkmcnt(0)
	v_pk_fma_f32 v[44:45], v[68:69], v[76:77], v[44:45] op_sel_hi:[1,0,1]
	s_nop 0
	v_pk_fma_f32 v[44:45], v[80:81], v[76:77], v[44:45] op_sel:[0,1,0]
	v_mov_b32_e32 v76, v79
	v_pk_fma_f32 v[44:45], v[82:83], v[78:79], v[44:45] op_sel_hi:[1,0,1]
	s_nop 0
	v_pk_fma_f32 v[44:45], v[84:85], v[76:77], v[44:45] op_sel_hi:[1,0,1]
	ds_read_b128 v[76:79], v15 offset:6144
	s_waitcnt lgkmcnt(0)
	v_pk_fma_f32 v[42:43], v[68:69], v[76:77], v[42:43] op_sel_hi:[1,0,1]
	s_nop 0
	v_pk_fma_f32 v[42:43], v[80:81], v[76:77], v[42:43] op_sel:[0,1,0]
	v_mov_b32_e32 v76, v79
	v_pk_fma_f32 v[42:43], v[82:83], v[78:79], v[42:43] op_sel_hi:[1,0,1]
	s_nop 0
	v_pk_fma_f32 v[42:43], v[84:85], v[76:77], v[42:43] op_sel_hi:[1,0,1]
	ds_read_b128 v[76:79], v15 offset:6656
	s_waitcnt lgkmcnt(0)
	v_pk_fma_f32 v[40:41], v[68:69], v[76:77], v[40:41] op_sel_hi:[1,0,1]
	s_nop 0
	v_pk_fma_f32 v[40:41], v[80:81], v[76:77], v[40:41] op_sel:[0,1,0]
	v_mov_b32_e32 v76, v79
	v_pk_fma_f32 v[40:41], v[82:83], v[78:79], v[40:41] op_sel_hi:[1,0,1]
	s_nop 0
	v_pk_fma_f32 v[40:41], v[84:85], v[76:77], v[40:41] op_sel_hi:[1,0,1]
	ds_read_b128 v[76:79], v15 offset:7168
	s_waitcnt lgkmcnt(0)
	v_pk_fma_f32 v[38:39], v[68:69], v[76:77], v[38:39] op_sel_hi:[1,0,1]
	s_nop 0
	v_pk_fma_f32 v[38:39], v[80:81], v[76:77], v[38:39] op_sel:[0,1,0]
	v_mov_b32_e32 v76, v79
	v_pk_fma_f32 v[38:39], v[82:83], v[78:79], v[38:39] op_sel_hi:[1,0,1]
	s_nop 0
	v_pk_fma_f32 v[38:39], v[84:85], v[76:77], v[38:39] op_sel_hi:[1,0,1]
	ds_read_b128 v[76:79], v15 offset:7680
	s_waitcnt lgkmcnt(0)
	v_pk_fma_f32 v[36:37], v[68:69], v[76:77], v[36:37] op_sel_hi:[1,0,1]
	s_nop 0
	v_pk_fma_f32 v[36:37], v[80:81], v[76:77], v[36:37] op_sel:[0,1,0]
	v_mov_b32_e32 v76, v79
	v_pk_fma_f32 v[36:37], v[82:83], v[78:79], v[36:37] op_sel_hi:[1,0,1]
	s_nop 0
	v_pk_fma_f32 v[36:37], v[84:85], v[76:77], v[36:37] op_sel_hi:[1,0,1]
	ds_read_b128 v[76:79], v15 offset:8192
	s_waitcnt lgkmcnt(0)
	v_pk_fma_f32 v[34:35], v[68:69], v[76:77], v[34:35] op_sel_hi:[1,0,1]
	s_nop 0
	v_pk_fma_f32 v[34:35], v[80:81], v[76:77], v[34:35] op_sel:[0,1,0]
	v_mov_b32_e32 v76, v79
	v_pk_fma_f32 v[34:35], v[82:83], v[78:79], v[34:35] op_sel_hi:[1,0,1]
	s_nop 0
	v_pk_fma_f32 v[34:35], v[84:85], v[76:77], v[34:35] op_sel_hi:[1,0,1]
	ds_read_b128 v[76:79], v15 offset:8704
	s_waitcnt lgkmcnt(0)
	v_pk_fma_f32 v[32:33], v[68:69], v[76:77], v[32:33] op_sel_hi:[1,0,1]
	s_nop 0
	v_pk_fma_f32 v[32:33], v[80:81], v[76:77], v[32:33] op_sel:[0,1,0]
	v_mov_b32_e32 v76, v79
	v_pk_fma_f32 v[32:33], v[82:83], v[78:79], v[32:33] op_sel_hi:[1,0,1]
	s_nop 0
	v_pk_fma_f32 v[32:33], v[84:85], v[76:77], v[32:33] op_sel_hi:[1,0,1]
	ds_read_b128 v[76:79], v15 offset:9216
	s_waitcnt lgkmcnt(0)
	v_pk_fma_f32 v[30:31], v[68:69], v[76:77], v[30:31] op_sel_hi:[1,0,1]
	s_nop 0
	v_pk_fma_f32 v[30:31], v[80:81], v[76:77], v[30:31] op_sel:[0,1,0]
	v_mov_b32_e32 v76, v79
	v_pk_fma_f32 v[30:31], v[82:83], v[78:79], v[30:31] op_sel_hi:[1,0,1]
	s_nop 0
	v_pk_fma_f32 v[30:31], v[84:85], v[76:77], v[30:31] op_sel_hi:[1,0,1]
	ds_read_b128 v[76:79], v15 offset:9728
	s_waitcnt lgkmcnt(0)
	v_pk_fma_f32 v[28:29], v[68:69], v[76:77], v[28:29] op_sel_hi:[1,0,1]
	s_nop 0
	v_pk_fma_f32 v[28:29], v[80:81], v[76:77], v[28:29] op_sel:[0,1,0]
	v_mov_b32_e32 v68, v79
	v_pk_fma_f32 v[28:29], v[82:83], v[78:79], v[28:29] op_sel_hi:[1,0,1]
	s_nop 0
	v_pk_fma_f32 v[28:29], v[84:85], v[68:69], v[28:29] op_sel_hi:[1,0,1]
	v_pk_fma_f32 v[66:67], v[88:89], v[6:7], v[66:67] op_sel_hi:[1,0,1]
	v_pk_fma_f32 v[6:7], v[90:91], v[6:7], v[66:67] op_sel:[0,1,0]
	v_pk_fma_f32 v[6:7], v[92:93], v[8:9], v[6:7] op_sel_hi:[1,0,1]
	v_mov_b32_e32 v8, v9
	v_pk_fma_f32 v[66:67], v[94:95], v[8:9], v[6:7] op_sel_hi:[1,0,1]
	ds_read_b128 v[6:9], v15 offset:528
	s_waitcnt lgkmcnt(0)
; #define LAS __attribute__((address_space(3)))
; __global__ void __launch_bounds__(NWAVES * 64, 2) mk_fwd(Args args) {
;     ...
;                     const float* wp = args.in[9] + ((size_t)lm * DM + k0) * (3 * DM) + col;
; #pragma unroll 2
;                     for (int k = 0; k < 128; k += 4) {
;                         const f32x2 wa = *(const f32x2*)(wp + (size_t)(k + 0) * (3 * DM)), wb = *(const f32x2*)(wp + (size_t)(k + 1) * (3 * DM));
;                         const f32x2 wc = *(const f32x2*)(wp + (size_t)(k + 2) * (3 * DM)), wd = *(const f32x2*)(wp + (size_t)(k + 3) * (3 * DM));
; #pragma unroll
;                         for (int r2 = 0; r2 < 20; ++r2) { const f32x4 cv = *(LAS const f32x4*)(cs + r2 * 128 + k);
;                             acc[r2] = wa * cv.x + acc[r2]; acc[r2] = wb * cv.y + acc[r2]; acc[r2] = wc * cv.z + acc[r2]; acc[r2] = wd * cv.w + acc[r2]; }
	v_pk_fma_f32 v[64:65], v[88:89], v[6:7], v[64:65] op_sel_hi:[1,0,1]
	s_nop 0
	v_pk_fma_f32 v[6:7], v[90:91], v[6:7], v[64:65] op_sel:[0,1,0]
	s_nop 0
	v_pk_fma_f32 v[6:7], v[92:93], v[8:9], v[6:7] op_sel_hi:[1,0,1]
	v_mov_b32_e32 v8, v9
	v_pk_fma_f32 v[64:65], v[94:95], v[8:9], v[6:7] op_sel_hi:[1,0,1]
	ds_read_b128 v[6:9], v15 offset:1040
	s_waitcnt lgkmcnt(0)
	v_pk_fma_f32 v[62:63], v[88:89], v[6:7], v[62:63] op_sel_hi:[1,0,1]
	s_nop 0
	v_pk_fma_f32 v[6:7], v[90:91], v[6:7], v[62:63] op_sel:[0,1,0]
	s_nop 0
	v_pk_fma_f32 v[6:7], v[92:93], v[8:9], v[6:7] op_sel_hi:[1,0,1]
	v_mov_b32_e32 v8, v9
	v_pk_fma_f32 v[62:63], v[94:95], v[8:9], v[6:7] op_sel_hi:[1,0,1]
	ds_read_b128 v[6:9], v15 offset:1552
	s_waitcnt lgkmcnt(0)
	v_pk_fma_f32 v[60:61], v[88:89], v[6:7], v[60:61] op_sel_hi:[1,0,1]
	s_nop 0
	v_pk_fma_f32 v[6:7], v[90:91], v[6:7], v[60:61] op_sel:[0,1,0]
	s_nop 0
	v_pk_fma_f32 v[6:7], v[92:93], v[8:9], v[6:7] op_sel_hi:[1,0,1]
	v_mov_b32_e32 v8, v9
	v_pk_fma_f32 v[60:61], v[94:95], v[8:9], v[6:7] op_sel_hi:[1,0,1]
	ds_read_b128 v[6:9], v15 offset:2064
	s_waitcnt lgkmcnt(0)
	v_pk_fma_f32 v[58:59], v[88:89], v[6:7], v[58:59] op_sel_hi:[1,0,1]
	s_nop 0
	v_pk_fma_f32 v[6:7], v[90:91], v[6:7], v[58:59] op_sel:[0,1,0]
	s_nop 0
	v_pk_fma_f32 v[6:7], v[92:93], v[8:9], v[6:7] op_sel_hi:[1,0,1]
	v_mov_b32_e32 v8, v9
	v_pk_fma_f32 v[58:59], v[94:95], v[8:9], v[6:7] op_sel_hi:[1,0,1]
	ds_read_b128 v[6:9], v15 offset:2576
	s_waitcnt lgkmcnt(0)
	v_pk_fma_f32 v[56:57], v[88:89], v[6:7], v[56:57] op_sel_hi:[1,0,1]
	s_nop 0
	v_pk_fma_f32 v[6:7], v[90:91], v[6:7], v[56:57] op_sel:[0,1,0]
	s_nop 0
	v_pk_fma_f32 v[6:7], v[92:93], v[8:9], v[6:7] op_sel_hi:[1,0,1]
	v_mov_b32_e32 v8, v9
	v_pk_fma_f32 v[56:57], v[94:95], v[8:9], v[6:7] op_sel_hi:[1,0,1]
	ds_read_b128 v[6:9], v15 offset:3088
	s_waitcnt lgkmcnt(0)
	v_pk_fma_f32 v[54:55], v[88:89], v[6:7], v[54:55] op_sel_hi:[1,0,1]
	s_nop 0
	v_pk_fma_f32 v[6:7], v[90:91], v[6:7], v[54:55] op_sel:[0,1,0]
	s_nop 0
	v_pk_fma_f32 v[6:7], v[92:93], v[8:9], v[6:7] op_sel_hi:[1,0,1]
	v_mov_b32_e32 v8, v9
	v_pk_fma_f32 v[54:55], v[94:95], v[8:9], v[6:7] op_sel_hi:[1,0,1]
	ds_read_b128 v[6:9], v15 offset:3600
	s_waitcnt lgkmcnt(0)
	v_pk_fma_f32 v[52:53], v[88:89], v[6:7], v[52:53] op_sel_hi:[1,0,1]
	s_nop 0
	v_pk_fma_f32 v[6:7], v[90:91], v[6:7], v[52:53] op_sel:[0,1,0]
	s_nop 0
	v_pk_fma_f32 v[6:7], v[92:93], v[8:9], v[6:7] op_sel_hi:[1,0,1]
	v_mov_b32_e32 v8, v9
	v_pk_fma_f32 v[52:53], v[94:95], v[8:9], v[6:7] op_sel_hi:[1,0,1]
	ds_read_b128 v[6:9], v15 offset:4112
	s_waitcnt lgkmcnt(0)
	v_pk_fma_f32 v[50:51], v[88:89], v[6:7], v[50:51] op_sel_hi:[1,0,1]
	s_nop 0
	v_pk_fma_f32 v[6:7], v[90:91], v[6:7], v[50:51] op_sel:[0,1,0]
	s_nop 0
	v_pk_fma_f32 v[6:7], v[92:93], v[8:9], v[6:7] op_sel_hi:[1,0,1]
	v_mov_b32_e32 v8, v9
	v_pk_fma_f32 v[50:51], v[94:95], v[8:9], v[6:7] op_sel_hi:[1,0,1]
	ds_read_b128 v[6:9], v15 offset:4624
	s_waitcnt lgkmcnt(0)
	v_pk_fma_f32 v[48:49], v[88:89], v[6:7], v[48:49] op_sel_hi:[1,0,1]
	s_nop 0
	v_pk_fma_f32 v[6:7], v[90:91], v[6:7], v[48:49] op_sel:[0,1,0]
	s_nop 0
	v_pk_fma_f32 v[6:7], v[92:93], v[8:9], v[6:7] op_sel_hi:[1,0,1]
	v_mov_b32_e32 v8, v9
	v_pk_fma_f32 v[48:49], v[94:95], v[8:9], v[6:7] op_sel_hi:[1,0,1]
	ds_read_b128 v[6:9], v15 offset:5136
	s_waitcnt lgkmcnt(0)
	v_pk_fma_f32 v[46:47], v[88:89], v[6:7], v[46:47] op_sel_hi:[1,0,1]
	s_nop 0
	v_pk_fma_f32 v[6:7], v[90:91], v[6:7], v[46:47] op_sel:[0,1,0]
	s_nop 0
	v_pk_fma_f32 v[6:7], v[92:93], v[8:9], v[6:7] op_sel_hi:[1,0,1]
	v_mov_b32_e32 v8, v9
	v_pk_fma_f32 v[46:47], v[94:95], v[8:9], v[6:7] op_sel_hi:[1,0,1]
	ds_read_b128 v[6:9], v15 offset:5648
	s_waitcnt lgkmcnt(0)
	v_pk_fma_f32 v[44:45], v[88:89], v[6:7], v[44:45] op_sel_hi:[1,0,1]
	s_nop 0
	v_pk_fma_f32 v[6:7], v[90:91], v[6:7], v[44:45] op_sel:[0,1,0]
	s_nop 0
	v_pk_fma_f32 v[6:7], v[92:93], v[8:9], v[6:7] op_sel_hi:[1,0,1]
	v_mov_b32_e32 v8, v9
	v_pk_fma_f32 v[44:45], v[94:95], v[8:9], v[6:7] op_sel_hi:[1,0,1]
	ds_read_b128 v[6:9], v15 offset:6160
	s_waitcnt lgkmcnt(0)
	v_pk_fma_f32 v[42:43], v[88:89], v[6:7], v[42:43] op_sel_hi:[1,0,1]
	s_nop 0
	v_pk_fma_f32 v[6:7], v[90:91], v[6:7], v[42:43] op_sel:[0,1,0]
	s_nop 0
	v_pk_fma_f32 v[6:7], v[92:93], v[8:9], v[6:7] op_sel_hi:[1,0,1]
	v_mov_b32_e32 v8, v9
	v_pk_fma_f32 v[42:43], v[94:95], v[8:9], v[6:7] op_sel_hi:[1,0,1]
	ds_read_b128 v[6:9], v15 offset:6672
	s_waitcnt lgkmcnt(0)
	v_pk_fma_f32 v[40:41], v[88:89], v[6:7], v[40:41] op_sel_hi:[1,0,1]
	s_nop 0
	v_pk_fma_f32 v[6:7], v[90:91], v[6:7], v[40:41] op_sel:[0,1,0]
	s_nop 0
	v_pk_fma_f32 v[6:7], v[92:93], v[8:9], v[6:7] op_sel_hi:[1,0,1]
	v_mov_b32_e32 v8, v9
	v_pk_fma_f32 v[40:41], v[94:95], v[8:9], v[6:7] op_sel_hi:[1,0,1]
	ds_read_b128 v[6:9], v15 offset:7184
	s_waitcnt lgkmcnt(0)
	v_pk_fma_f32 v[38:39], v[88:89], v[6:7], v[38:39] op_sel_hi:[1,0,1]
	s_nop 0
	v_pk_fma_f32 v[6:7], v[90:91], v[6:7], v[38:39] op_sel:[0,1,0]
	s_nop 0
	v_pk_fma_f32 v[6:7], v[92:93], v[8:9], v[6:7] op_sel_hi:[1,0,1]
	v_mov_b32_e32 v8, v9
	v_pk_fma_f32 v[38:39], v[94:95], v[8:9], v[6:7] op_sel_hi:[1,0,1]
	ds_read_b128 v[6:9], v15 offset:7696
	s_waitcnt lgkmcnt(0)
	v_pk_fma_f32 v[36:37], v[88:89], v[6:7], v[36:37] op_sel_hi:[1,0,1]
	s_nop 0
	v_pk_fma_f32 v[6:7], v[90:91], v[6:7], v[36:37] op_sel:[0,1,0]
	s_nop 0
	v_pk_fma_f32 v[6:7], v[92:93], v[8:9], v[6:7] op_sel_hi:[1,0,1]
	v_mov_b32_e32 v8, v9
	v_pk_fma_f32 v[36:37], v[94:95], v[8:9], v[6:7] op_sel_hi:[1,0,1]
	ds_read_b128 v[6:9], v15 offset:8208
	s_waitcnt lgkmcnt(0)
	v_pk_fma_f32 v[34:35], v[88:89], v[6:7], v[34:35] op_sel_hi:[1,0,1]
	s_nop 0
	v_pk_fma_f32 v[6:7], v[90:91], v[6:7], v[34:35] op_sel:[0,1,0]
	s_nop 0
	v_pk_fma_f32 v[6:7], v[92:93], v[8:9], v[6:7] op_sel_hi:[1,0,1]
	v_mov_b32_e32 v8, v9
	v_pk_fma_f32 v[34:35], v[94:95], v[8:9], v[6:7] op_sel_hi:[1,0,1]
	ds_read_b128 v[6:9], v15 offset:8720
	s_waitcnt lgkmcnt(0)
	v_pk_fma_f32 v[32:33], v[88:89], v[6:7], v[32:33] op_sel_hi:[1,0,1]
	s_nop 0
	v_pk_fma_f32 v[6:7], v[90:91], v[6:7], v[32:33] op_sel:[0,1,0]
	s_nop 0
	v_pk_fma_f32 v[6:7], v[92:93], v[8:9], v[6:7] op_sel_hi:[1,0,1]
	v_mov_b32_e32 v8, v9
	v_pk_fma_f32 v[32:33], v[94:95], v[8:9], v[6:7] op_sel_hi:[1,0,1]
	ds_read_b128 v[6:9], v15 offset:9232
	s_waitcnt lgkmcnt(0)
	v_pk_fma_f32 v[30:31], v[88:89], v[6:7], v[30:31] op_sel_hi:[1,0,1]
	s_nop 0
	v_pk_fma_f32 v[6:7], v[90:91], v[6:7], v[30:31] op_sel:[0,1,0]
	s_nop 0
	v_pk_fma_f32 v[6:7], v[92:93], v[8:9], v[6:7] op_sel_hi:[1,0,1]
	v_mov_b32_e32 v8, v9
	v_pk_fma_f32 v[30:31], v[94:95], v[8:9], v[6:7] op_sel_hi:[1,0,1]
	ds_read_b128 v[6:9], v15 offset:9744
	s_waitcnt lgkmcnt(0)
	v_pk_fma_f32 v[28:29], v[88:89], v[6:7], v[28:29] op_sel_hi:[1,0,1]
	s_nop 0
	v_pk_fma_f32 v[6:7], v[90:91], v[6:7], v[28:29] op_sel:[0,1,0]
	s_nop 0
	v_pk_fma_f32 v[6:7], v[92:93], v[8:9], v[6:7] op_sel_hi:[1,0,1]
	v_mov_b32_e32 v8, v9
	v_pk_fma_f32 v[28:29], v[94:95], v[8:9], v[6:7] op_sel_hi:[1,0,1]
	s_cbranch_scc0 .LBB0_29
; __global__ void __launch_bounds__(NWAVES * 64, 2) mk_fwd(Args args) {
;     ...
;                 }
;                 float* mp = modp + ((size_t)(lm * 11 + sl) * 20) * (3 * DM) + col;
; #pragma unroll
;                 for (int r2 = 0; r2 < 20; ++r2) *(f32x2*)(mp + (size_t)r2 * (3 * DM)) = acc[r2];
;             }
	s_add_i32 s40, s40, s36
	s_add_i32 s38, s38, s39
	s_cmp_gt_i32 s40, 31
	s_cbranch_scc0 .LBB0_18
	s_mul_i32 s37, s37, 11
	s_sext_i32_i8 s0, s37
	s_add_i32 s0, s35, s0
	s_mul_hi_i32 s1, s0, 0xf0000
	s_mul_i32 s0, s0, 0xf0000
	s_add_u32 s0, s15, s0
	s_addc_u32 s1, s28, s1
	v_lshl_add_u64 v[6:7], v[22:23], 2, s[0:1]
	v_add_co_u32_e32 v8, vcc, 0xc000, v6
	global_store_dwordx2 v[6:7], v[66:67], off
	s_nop 0
	v_addc_co_u32_e32 v9, vcc, 0, v7, vcc
	global_store_dwordx2 v[8:9], v[64:65], off
	v_add_co_u32_e32 v8, vcc, 0x18000, v6
	s_add_i32 s34, s34, s25
	s_nop 0
	v_addc_co_u32_e32 v9, vcc, 0, v7, vcc
	global_store_dwordx2 v[8:9], v[62:63], off
	v_add_co_u32_e32 v8, vcc, 0x24000, v6
	s_cmpk_gt_i32 s34, 0xff
	s_nop 0
	v_addc_co_u32_e32 v9, vcc, 0, v7, vcc
	global_store_dwordx2 v[8:9], v[60:61], off
	v_add_co_u32_e32 v8, vcc, 0x30000, v6
	s_nop 1
	v_addc_co_u32_e32 v9, vcc, 0, v7, vcc
	global_store_dwordx2 v[8:9], v[58:59], off
	v_add_co_u32_e32 v8, vcc, 0x3c000, v6
	s_nop 1
	v_addc_co_u32_e32 v9, vcc, 0, v7, vcc
	global_store_dwordx2 v[8:9], v[56:57], off
	v_add_co_u32_e32 v8, vcc, 0x48000, v6
	s_nop 1
	v_addc_co_u32_e32 v9, vcc, 0, v7, vcc
	global_store_dwordx2 v[8:9], v[54:55], off
	v_add_co_u32_e32 v8, vcc, 0x54000, v6
	s_nop 1
	v_addc_co_u32_e32 v9, vcc, 0, v7, vcc
	global_store_dwordx2 v[8:9], v[52:53], off
	v_add_co_u32_e32 v8, vcc, 0x60000, v6
	s_nop 1
	v_addc_co_u32_e32 v9, vcc, 0, v7, vcc
	global_store_dwordx2 v[8:9], v[50:51], off
	v_add_co_u32_e32 v8, vcc, 0x6c000, v6
	s_nop 1
	v_addc_co_u32_e32 v9, vcc, 0, v7, vcc
	global_store_dwordx2 v[8:9], v[48:49], off
	v_add_co_u32_e32 v8, vcc, 0x78000, v6
	s_nop 1
	v_addc_co_u32_e32 v9, vcc, 0, v7, vcc
	global_store_dwordx2 v[8:9], v[46:47], off
	v_add_co_u32_e32 v8, vcc, 0x84000, v6
	s_nop 1
	v_addc_co_u32_e32 v9, vcc, 0, v7, vcc
	global_store_dwordx2 v[8:9], v[44:45], off
	v_add_co_u32_e32 v8, vcc, 0x90000, v6
	s_nop 1
	v_addc_co_u32_e32 v9, vcc, 0, v7, vcc
	global_store_dwordx2 v[8:9], v[42:43], off
	v_add_co_u32_e32 v8, vcc, 0x9c000, v6
	s_nop 1
	v_addc_co_u32_e32 v9, vcc, 0, v7, vcc
	global_store_dwordx2 v[8:9], v[40:41], off
	v_add_co_u32_e32 v8, vcc, 0xa8000, v6
	s_nop 1
	v_addc_co_u32_e32 v9, vcc, 0, v7, vcc
	global_store_dwordx2 v[8:9], v[38:39], off
	v_add_co_u32_e32 v8, vcc, 0xb4000, v6
	s_nop 1
	v_addc_co_u32_e32 v9, vcc, 0, v7, vcc
	global_store_dwordx2 v[8:9], v[36:37], off
	v_add_co_u32_e32 v8, vcc, 0xc0000, v6
	s_nop 1
	v_addc_co_u32_e32 v9, vcc, 0, v7, vcc
	global_store_dwordx2 v[8:9], v[34:35], off
	v_add_co_u32_e32 v8, vcc, 0xcc000, v6
	s_nop 1
	v_addc_co_u32_e32 v9, vcc, 0, v7, vcc
	global_store_dwordx2 v[8:9], v[32:33], off
	v_add_co_u32_e32 v8, vcc, 0xd8000, v6
	s_nop 1
	v_addc_co_u32_e32 v9, vcc, 0, v7, vcc
	v_add_co_u32_e32 v6, vcc, 0xe4000, v6
	global_store_dwordx2 v[8:9], v[30:31], off
	s_nop 0
	v_addc_co_u32_e32 v7, vcc, 0, v7, vcc
	global_store_dwordx2 v[6:7], v[28:29], off
	s_cbranch_scc0 .LBB0_17
